# stack19 + attention: first sub-block's Q-fragment loads issued before the K/V staging barrier (overlap the LDS-write drain and barrier wait)
# speedup vs baseline: 1.0039x; 1.0039x over previous
.LBB0_239:
	s_or_b64 exec, exec, s[62:63]
	s_add_i32 s0, s98, s18
	s_lshl_b32 s62, s0, 6
	s_ashr_i32 s63, s62, 31
	s_lshl_b64 s[64:65], s[62:63], 1
	s_add_u32 s16, s16, s64
	s_addc_u32 s17, s17, s65
	s_ashr_i32 s1, s0, 31
	s_lshl_b64 s[0:1], s[0:1], 2
	s_add_u32 s62, s2, s0
	s_addc_u32 s63, s3, s1
	s_or_b32 s66, s72, s90
	v_mov_b32_e32 v91, v1
	v_or_b32_e32 v0, s66, v87
	s_waitcnt vmcnt(0)
	v_mov_b64_e32 v[2:3], s[58:59]
	v_lshl_add_u64 v[98:99], s[16:17], 0, v[90:91]
	v_mad_u64_u32 v[94:95], s[16:17], v0, s93, v[2:3]
	v_lshrrev_b32_e32 v216, 5, v158
	v_and_or_b32 v217, v94, -4, v216
	v_mad_u64_u32 v[2:3], s[16:17], v217, s19, 0
	v_mov_b32_e32 v0, v3
	v_mad_u64_u32 v[4:5], s[16:17], v95, s19, v[0:1]
	v_mov_b32_e32 v3, v4
	v_lshl_add_u64 v[2:3], v[2:3], 1, v[98:99]
	v_and_b32_e32 v218, 3, v94
	v_sub_u32_e32 v218, v218, v216
	v_lshlrev_b32_e32 v218, 4, v218
	v_ashrrev_i32_e32 v219, 31, v218
	v_lshl_add_u64 v[2:3], v[2:3], 0, v[218:219]
	v_lshlrev_b32_e64 v220, 2, s19
	v_mov_b32_e32 v221, 0
	v_lshl_add_u64 v[220:221], v[2:3], 0, v[220:221]
	global_load_dwordx4 v[64:67], v[2:3], off
	global_load_dwordx4 v[68:71], v[220:221], off
	global_load_dwordx4 v[72:75], v[2:3], off offset:64
	global_load_dwordx4 v[76:79], v[220:221], off offset:64
	s_waitcnt lgkmcnt(0)
	s_barrier
	v_cndmask_b32_e64 v0, 0, 1, s[52:53]
	v_cmp_ne_u32_e64 s[16:17], 1, v0
	s_andn2_b64 vcc, exec, s[52:53]
	s_cbranch_vccnz .LBB0_241
	global_load_dword v0, v1, s[62:63]
	v_mov_b32_e32 v138, v89
	s_waitcnt vmcnt(0)
	v_mul_f32_e32 v93, 0x3fb8aa3b, v0
	s_branch .LBB0_242
